# sample-stream RWKV scan rewritten: 4 compute waves + 4 LDS-DMA loader waves per block, shared 5-slot LDS ring, deferred transposing output reduction
# speedup vs baseline: 1.0611x; 1.0611x over previous
.LBB0_583:
	s_andn2_b64 vcc, exec, s[0:1]
	s_cbranch_vccnz .LBB0_597
	v_readfirstlane_b32 s0, v89
	v_readlane_b32 s70, v253, 52
	s_mov_b32 s71, s2
	s_lshr_b32 s70, s70, 2
.Lss_task_loop:
	s_cmp_ge_u32 s71, 0x80
	s_cbranch_scc1 .Lss_done
	s_lshr_b32 s20, s71, 3
	s_bfe_u32 s21, s71, 0x10002
	s_cmp_ge_u32 s0, 4
	s_cbranch_scc1 .Lss_loader
	s_and_b32 s22, s71, 3
	s_lshl_b32 s22, s22, 4
	s_lshl_b32 s23, s0, 2
	s_add_u32 s22, s22, s23
	v_and_b32_e32 v6, 15, v0
	v_bfe_u32 v7, v0, 4, 2
	ds_read_b64 v[10:11], v131 offset:32
	v_lshlrev_b32_e32 v124, 4, v6
	v_add_u32_e32 v8, s22, v7
	v_add_u32_e32 v124, 0xf0, v124
	v_lshlrev_b32_e32 v130, 2, v8
	v_add_u32_e32 v130, 0x2f0, v130
	s_lshr_b32 s23, s20, 2
	s_and_b32 s24, s20, 3
	s_lshl_b32 s23, s23, 1
	s_add_u32 s23, s23, s80
	s_lshl_b32 s23, s23, 1
	s_add_u32 s23, s23, s21
	s_lshl_b32 s23, s23, 2
	s_add_u32 s23, s23, s24
	s_lshl_b32 s23, s23, 14
	v_lshlrev_b32_e32 v9, 8, v8
	v_lshl_add_u32 v9, v6, 4, v9
	s_waitcnt lgkmcnt(0)
	v_readfirstlane_b32 s24, v10
	v_readfirstlane_b32 s25, v11
	s_nop 3
	s_add_u32 s24, s24, s23
	s_addc_u32 s25, s25, 0
	s_nop 3
	global_load_dwordx4 v[2:5], v9, s[24:25]
	v_readlane_b32 s4, v253, 47
	v_readlane_b32 s5, v253, 48
	s_lshl_b32 s23, s21, 23
	s_lshr_b32 s24, s20, 2
	s_lshl_b32 s24, s24, 20
	s_add_u32 s23, s23, s24
	s_add_u32 s23, s23, 0x400000
	s_and_b32 s24, s20, 3
	s_lshl_b32 s24, s24, 8
	s_add_u32 s23, s23, s24
	s_lshl_b32 s24, s22, 2
	s_add_u32 s23, s23, s24
	s_add_u32 s4, s4, s23
	s_addc_u32 s5, s5, 0
	s_cmp_eq_u32 s21, 1
	s_cselect_b64 s[24:25], -1, 0
	s_mov_b32 s6, 0x4000
	s_cselect_b32 s6, 0xffffc000, s6
	s_cselect_b32 s7, -1, 0
	v_sub_u32_e32 v9, 0x3ff, v6
	v_cndmask_b32_e64 v10, v6, v9, s[24:25]
	v_lshlrev_b32_e32 v10, 10, v10
	v_lshl_add_u32 v111, v7, 2, v10
	s_mov_b32 s10, 0xcccccccc
	s_mov_b32 s11, 0xcccccccc
	s_mov_b32 s14, 0xaaaaaaaa
	s_mov_b32 s15, 0xaaaaaaaa
	s_mov_b32 s8, 0
	s_mov_b32 s1, 64
	v_mov_b32_e32 v27, v124
	v_mov_b32_e32 v49, v130
	s_barrier
	ds_read_b128 v[6:9], v27 offset:256
	ds_read_b128 v[10:13], v27 offset:12288
	ds_read_b128 v[14:17], v27 offset:12544
	ds_read_b128 v[18:21], v27 offset:12800
	ds_read_b128 v[22:25], v27 offset:0
	ds_read_b32 v26, v49 offset:0
	ds_read_b128 v[28:31], v27 offset:1024
	ds_read_b128 v[32:35], v27 offset:13056
	ds_read_b128 v[36:39], v27 offset:13312
	ds_read_b128 v[40:43], v27 offset:13568
	ds_read_b128 v[44:47], v27 offset:768
	ds_read_b32 v48, v49 offset:768
	s_waitcnt vmcnt(0)
.Lss_c_loop:
	s_barrier
	s_add_u32 s9, s8, 0x6000
	s_cmp_eq_u32 s9, 0x1e000
	s_cselect_b32 s9, 0, s9
	v_add_u32_e32 v71, s9, v124
	v_add_u32_e32 v93, s9, v130
	s_waitcnt lgkmcnt(6)
	v_pk_mul_f32 v[114:115], v[4:5], v[8:9]
	v_pk_mul_f32 v[118:119], v[18:19], v[26:27] op_sel_hi:[1,0]
	v_pk_fma_f32 v[114:115], v[2:3], v[6:7], v[114:115]
	v_pk_mul_f32 v[120:121], v[20:21], v[26:27] op_sel_hi:[1,0]
	v_add_f32_e32 v112, v114, v115
	v_pk_fma_f32 v[118:119], v[2:3], v[10:11], v[118:119]
	v_pk_fma_f32 v[120:121], v[4:5], v[12:13], v[120:121]
	v_add_f32_dpp v112, v112, v112 row_ror:8 row_mask:0xf bank_mask:0xf
	ds_read_b128 v[50:53], v27 offset:1792
	ds_read_b128 v[54:57], v27 offset:13824
	v_add_f32_dpp v112, v112, v112 row_ror:4 row_mask:0xf bank_mask:0xf
	ds_read_b128 v[58:61], v27 offset:14080
	ds_read_b128 v[62:65], v27 offset:14336
	v_add_f32_dpp v112, v112, v112 row_ror:2 row_mask:0xf bank_mask:0xf
	ds_read_b128 v[66:69], v27 offset:1536
	ds_read_b32 v70, v49 offset:1536
	v_add_f32_dpp v112, v112, v112 row_ror:1 row_mask:0xf bank_mask:0xf
	v_pk_fma_f32 v[4:5], v[16:17], v[112:113], v[120:121] op_sel_hi:[1,0,1]
	v_pk_fma_f32 v[2:3], v[14:15], v[112:113], v[118:119] op_sel_hi:[1,0,1]
	s_waitcnt lgkmcnt(6)
	v_pk_mul_f32 v[114:115], v[4:5], v[30:31]
	v_pk_mul_f32 v[116:117], v[4:5], v[24:25]
	v_pk_fma_f32 v[114:115], v[2:3], v[28:29], v[114:115]
	v_pk_fma_f32 v[116:117], v[2:3], v[22:23], v[116:117]
	v_add_f32_e32 v112, v114, v115
	v_add_f32_e32 v94, v116, v117
	v_pk_mul_f32 v[118:119], v[40:41], v[48:49] op_sel_hi:[1,0]
	v_add_f32_dpp v112, v112, v112 row_ror:8 row_mask:0xf bank_mask:0xf
	v_pk_mul_f32 v[120:121], v[42:43], v[48:49] op_sel_hi:[1,0]
	v_pk_fma_f32 v[118:119], v[2:3], v[32:33], v[118:119]
	v_add_f32_dpp v112, v112, v112 row_ror:4 row_mask:0xf bank_mask:0xf
	v_pk_fma_f32 v[120:121], v[4:5], v[34:35], v[120:121]
	ds_read_b128 v[72:75], v27 offset:2560
	v_add_f32_dpp v112, v112, v112 row_ror:2 row_mask:0xf bank_mask:0xf
	ds_read_b128 v[76:79], v27 offset:14592
	ds_read_b128 v[80:83], v27 offset:14848
	v_add_f32_dpp v112, v112, v112 row_ror:1 row_mask:0xf bank_mask:0xf
	ds_read_b128 v[84:87], v27 offset:15104
	ds_read_b128 v[88:91], v27 offset:2304
	ds_read_b32 v92, v49 offset:2304
	v_pk_fma_f32 v[4:5], v[38:39], v[112:113], v[120:121] op_sel_hi:[1,0,1]
	v_pk_fma_f32 v[2:3], v[36:37], v[112:113], v[118:119] op_sel_hi:[1,0,1]
	s_waitcnt lgkmcnt(6)
	v_pk_mul_f32 v[114:115], v[4:5], v[52:53]
	v_pk_mul_f32 v[116:117], v[4:5], v[46:47]
	v_pk_fma_f32 v[114:115], v[2:3], v[50:51], v[114:115]
	v_pk_fma_f32 v[116:117], v[2:3], v[44:45], v[116:117]
	v_add_f32_e32 v112, v114, v115
	v_add_f32_e32 v95, v116, v117
	v_pk_mul_f32 v[118:119], v[62:63], v[70:71] op_sel_hi:[1,0]
	v_add_f32_dpp v112, v112, v112 row_ror:8 row_mask:0xf bank_mask:0xf
	v_pk_mul_f32 v[120:121], v[64:65], v[70:71] op_sel_hi:[1,0]
	v_pk_fma_f32 v[118:119], v[2:3], v[54:55], v[118:119]
	v_add_f32_dpp v112, v112, v112 row_ror:4 row_mask:0xf bank_mask:0xf
	v_pk_fma_f32 v[120:121], v[4:5], v[56:57], v[120:121]
	ds_read_b128 v[6:9], v27 offset:3328
	v_add_f32_dpp v112, v112, v112 row_ror:2 row_mask:0xf bank_mask:0xf
	ds_read_b128 v[10:13], v27 offset:15360
	ds_read_b128 v[14:17], v27 offset:15616
	v_add_f32_dpp v112, v112, v112 row_ror:1 row_mask:0xf bank_mask:0xf
	ds_read_b128 v[18:21], v27 offset:15872
	ds_read_b128 v[22:25], v27 offset:3072
	ds_read_b32 v26, v49 offset:3072
	v_pk_fma_f32 v[4:5], v[60:61], v[112:113], v[120:121] op_sel_hi:[1,0,1]
	v_pk_fma_f32 v[2:3], v[58:59], v[112:113], v[118:119] op_sel_hi:[1,0,1]
	s_waitcnt lgkmcnt(6)
	v_pk_mul_f32 v[114:115], v[4:5], v[74:75]
	v_pk_mul_f32 v[116:117], v[4:5], v[68:69]
	v_pk_fma_f32 v[114:115], v[2:3], v[72:73], v[114:115]
	v_pk_fma_f32 v[116:117], v[2:3], v[66:67], v[116:117]
	v_add_f32_e32 v112, v114, v115
	v_add_f32_e32 v96, v116, v117
	v_pk_mul_f32 v[118:119], v[84:85], v[92:93] op_sel_hi:[1,0]
	v_add_f32_dpp v112, v112, v112 row_ror:8 row_mask:0xf bank_mask:0xf
	v_pk_mul_f32 v[120:121], v[86:87], v[92:93] op_sel_hi:[1,0]
	v_pk_fma_f32 v[118:119], v[2:3], v[76:77], v[118:119]
	v_add_f32_dpp v112, v112, v112 row_ror:4 row_mask:0xf bank_mask:0xf
	v_pk_fma_f32 v[120:121], v[4:5], v[78:79], v[120:121]
	ds_read_b128 v[28:31], v27 offset:4096
	v_add_f32_dpp v112, v112, v112 row_ror:2 row_mask:0xf bank_mask:0xf
	ds_read_b128 v[32:35], v27 offset:16128
	ds_read_b128 v[36:39], v27 offset:16384
	v_add_f32_dpp v112, v112, v112 row_ror:1 row_mask:0xf bank_mask:0xf
	ds_read_b128 v[40:43], v27 offset:16640
	ds_read_b128 v[44:47], v27 offset:3840
	ds_read_b32 v48, v49 offset:3840
	v_pk_fma_f32 v[4:5], v[82:83], v[112:113], v[120:121] op_sel_hi:[1,0,1]
	v_pk_fma_f32 v[2:3], v[80:81], v[112:113], v[118:119] op_sel_hi:[1,0,1]
	s_waitcnt lgkmcnt(6)
	v_pk_mul_f32 v[114:115], v[4:5], v[8:9]
	v_pk_mul_f32 v[116:117], v[4:5], v[90:91]
	v_pk_fma_f32 v[114:115], v[2:3], v[6:7], v[114:115]
	v_pk_fma_f32 v[116:117], v[2:3], v[88:89], v[116:117]
	v_add_f32_e32 v112, v114, v115
	v_add_f32_e32 v97, v116, v117
	v_pk_mul_f32 v[118:119], v[18:19], v[26:27] op_sel_hi:[1,0]
	v_add_f32_dpp v112, v112, v112 row_ror:8 row_mask:0xf bank_mask:0xf
	v_pk_mul_f32 v[120:121], v[20:21], v[26:27] op_sel_hi:[1,0]
	v_pk_fma_f32 v[118:119], v[2:3], v[10:11], v[118:119]
	v_add_f32_dpp v112, v112, v112 row_ror:4 row_mask:0xf bank_mask:0xf
	v_pk_fma_f32 v[120:121], v[4:5], v[12:13], v[120:121]
	ds_read_b128 v[50:53], v27 offset:4864
	v_add_f32_dpp v112, v112, v112 row_ror:2 row_mask:0xf bank_mask:0xf
	ds_read_b128 v[54:57], v27 offset:16896
	ds_read_b128 v[58:61], v27 offset:17152
	v_add_f32_dpp v112, v112, v112 row_ror:1 row_mask:0xf bank_mask:0xf
	ds_read_b128 v[62:65], v27 offset:17408
	ds_read_b128 v[66:69], v27 offset:4608
	ds_read_b32 v70, v49 offset:4608
	v_pk_fma_f32 v[4:5], v[16:17], v[112:113], v[120:121] op_sel_hi:[1,0,1]
	v_pk_fma_f32 v[2:3], v[14:15], v[112:113], v[118:119] op_sel_hi:[1,0,1]
	s_waitcnt lgkmcnt(6)
	v_pk_mul_f32 v[114:115], v[4:5], v[30:31]
	v_pk_mul_f32 v[116:117], v[4:5], v[24:25]
	v_pk_fma_f32 v[114:115], v[2:3], v[28:29], v[114:115]
	v_pk_fma_f32 v[116:117], v[2:3], v[22:23], v[116:117]
	v_add_f32_e32 v112, v114, v115
	v_add_f32_e32 v98, v116, v117
	v_pk_mul_f32 v[118:119], v[40:41], v[48:49] op_sel_hi:[1,0]
	v_add_f32_dpp v112, v112, v112 row_ror:8 row_mask:0xf bank_mask:0xf
	v_pk_mul_f32 v[120:121], v[42:43], v[48:49] op_sel_hi:[1,0]
	v_pk_fma_f32 v[118:119], v[2:3], v[32:33], v[118:119]
	v_add_f32_dpp v112, v112, v112 row_ror:4 row_mask:0xf bank_mask:0xf
	v_pk_fma_f32 v[120:121], v[4:5], v[34:35], v[120:121]
	ds_read_b128 v[72:75], v27 offset:5632
	v_add_f32_dpp v112, v112, v112 row_ror:2 row_mask:0xf bank_mask:0xf
	ds_read_b128 v[76:79], v27 offset:17664
	ds_read_b128 v[80:83], v27 offset:17920
	v_add_f32_dpp v112, v112, v112 row_ror:1 row_mask:0xf bank_mask:0xf
	ds_read_b128 v[84:87], v27 offset:18176
	ds_read_b128 v[88:91], v27 offset:5376
	ds_read_b32 v92, v49 offset:5376
	v_pk_fma_f32 v[4:5], v[38:39], v[112:113], v[120:121] op_sel_hi:[1,0,1]
	v_pk_fma_f32 v[2:3], v[36:37], v[112:113], v[118:119] op_sel_hi:[1,0,1]
	s_waitcnt lgkmcnt(6)
	v_pk_mul_f32 v[114:115], v[4:5], v[52:53]
	v_pk_mul_f32 v[116:117], v[4:5], v[46:47]
	v_pk_fma_f32 v[114:115], v[2:3], v[50:51], v[114:115]
	v_pk_fma_f32 v[116:117], v[2:3], v[44:45], v[116:117]
	v_add_f32_e32 v112, v114, v115
	v_add_f32_e32 v99, v116, v117
	v_pk_mul_f32 v[118:119], v[62:63], v[70:71] op_sel_hi:[1,0]
	v_add_f32_dpp v112, v112, v112 row_ror:8 row_mask:0xf bank_mask:0xf
	v_pk_mul_f32 v[120:121], v[64:65], v[70:71] op_sel_hi:[1,0]
	v_pk_fma_f32 v[118:119], v[2:3], v[54:55], v[118:119]
	v_add_f32_dpp v112, v112, v112 row_ror:4 row_mask:0xf bank_mask:0xf
	v_pk_fma_f32 v[120:121], v[4:5], v[56:57], v[120:121]
	ds_read_b128 v[6:9], v27 offset:6400
	v_add_f32_dpp v112, v112, v112 row_ror:2 row_mask:0xf bank_mask:0xf
	ds_read_b128 v[10:13], v27 offset:18432
	ds_read_b128 v[14:17], v27 offset:18688
	v_add_f32_dpp v112, v112, v112 row_ror:1 row_mask:0xf bank_mask:0xf
	ds_read_b128 v[18:21], v27 offset:18944
	ds_read_b128 v[22:25], v27 offset:6144
	ds_read_b32 v26, v49 offset:6144
	v_pk_fma_f32 v[4:5], v[60:61], v[112:113], v[120:121] op_sel_hi:[1,0,1]
	v_pk_fma_f32 v[2:3], v[58:59], v[112:113], v[118:119] op_sel_hi:[1,0,1]
	s_waitcnt lgkmcnt(6)
	v_pk_mul_f32 v[114:115], v[4:5], v[74:75]
	v_pk_mul_f32 v[116:117], v[4:5], v[68:69]
	v_pk_fma_f32 v[114:115], v[2:3], v[72:73], v[114:115]
	v_pk_fma_f32 v[116:117], v[2:3], v[66:67], v[116:117]
	v_add_f32_e32 v112, v114, v115
	v_add_f32_e32 v100, v116, v117
	v_pk_mul_f32 v[118:119], v[84:85], v[92:93] op_sel_hi:[1,0]
	v_add_f32_dpp v112, v112, v112 row_ror:8 row_mask:0xf bank_mask:0xf
	v_pk_mul_f32 v[120:121], v[86:87], v[92:93] op_sel_hi:[1,0]
	v_pk_fma_f32 v[118:119], v[2:3], v[76:77], v[118:119]
	v_add_f32_dpp v112, v112, v112 row_ror:4 row_mask:0xf bank_mask:0xf
	v_pk_fma_f32 v[120:121], v[4:5], v[78:79], v[120:121]
	ds_read_b128 v[28:31], v27 offset:7168
	v_add_f32_dpp v112, v112, v112 row_ror:2 row_mask:0xf bank_mask:0xf
	ds_read_b128 v[32:35], v27 offset:19200
	ds_read_b128 v[36:39], v27 offset:19456
	v_add_f32_dpp v112, v112, v112 row_ror:1 row_mask:0xf bank_mask:0xf
	ds_read_b128 v[40:43], v27 offset:19712
	ds_read_b128 v[44:47], v27 offset:6912
	ds_read_b32 v48, v49 offset:6912
	v_pk_fma_f32 v[4:5], v[82:83], v[112:113], v[120:121] op_sel_hi:[1,0,1]
	v_pk_fma_f32 v[2:3], v[80:81], v[112:113], v[118:119] op_sel_hi:[1,0,1]
	s_waitcnt lgkmcnt(6)
	v_pk_mul_f32 v[114:115], v[4:5], v[8:9]
	v_pk_mul_f32 v[116:117], v[4:5], v[90:91]
	v_pk_fma_f32 v[114:115], v[2:3], v[6:7], v[114:115]
	v_pk_fma_f32 v[116:117], v[2:3], v[88:89], v[116:117]
	v_add_f32_e32 v112, v114, v115
	v_add_f32_e32 v101, v116, v117
	v_pk_mul_f32 v[118:119], v[18:19], v[26:27] op_sel_hi:[1,0]
	v_add_f32_dpp v112, v112, v112 row_ror:8 row_mask:0xf bank_mask:0xf
	v_pk_mul_f32 v[120:121], v[20:21], v[26:27] op_sel_hi:[1,0]
	v_pk_fma_f32 v[118:119], v[2:3], v[10:11], v[118:119]
	v_add_f32_dpp v112, v112, v112 row_ror:4 row_mask:0xf bank_mask:0xf
	v_pk_fma_f32 v[120:121], v[4:5], v[12:13], v[120:121]
	ds_read_b128 v[50:53], v27 offset:7936
	v_add_f32_dpp v112, v112, v112 row_ror:2 row_mask:0xf bank_mask:0xf
	ds_read_b128 v[54:57], v27 offset:19968
	ds_read_b128 v[58:61], v27 offset:20224
	v_add_f32_dpp v112, v112, v112 row_ror:1 row_mask:0xf bank_mask:0xf
	ds_read_b128 v[62:65], v27 offset:20480
	ds_read_b128 v[66:69], v27 offset:7680
	ds_read_b32 v70, v49 offset:7680
	v_pk_fma_f32 v[4:5], v[16:17], v[112:113], v[120:121] op_sel_hi:[1,0,1]
	v_pk_fma_f32 v[2:3], v[14:15], v[112:113], v[118:119] op_sel_hi:[1,0,1]
	s_waitcnt lgkmcnt(6)
	v_pk_mul_f32 v[114:115], v[4:5], v[30:31]
	v_pk_mul_f32 v[116:117], v[4:5], v[24:25]
	v_pk_fma_f32 v[114:115], v[2:3], v[28:29], v[114:115]
	v_pk_fma_f32 v[116:117], v[2:3], v[22:23], v[116:117]
	v_add_f32_e32 v112, v114, v115
	v_add_f32_e32 v102, v116, v117
	v_pk_mul_f32 v[118:119], v[40:41], v[48:49] op_sel_hi:[1,0]
	v_add_f32_dpp v112, v112, v112 row_ror:8 row_mask:0xf bank_mask:0xf
	v_pk_mul_f32 v[120:121], v[42:43], v[48:49] op_sel_hi:[1,0]
	v_pk_fma_f32 v[118:119], v[2:3], v[32:33], v[118:119]
	v_add_f32_dpp v112, v112, v112 row_ror:4 row_mask:0xf bank_mask:0xf
	v_pk_fma_f32 v[120:121], v[4:5], v[34:35], v[120:121]
	ds_read_b128 v[72:75], v27 offset:8704
	v_add_f32_dpp v112, v112, v112 row_ror:2 row_mask:0xf bank_mask:0xf
	ds_read_b128 v[76:79], v27 offset:20736
	ds_read_b128 v[80:83], v27 offset:20992
	v_add_f32_dpp v112, v112, v112 row_ror:1 row_mask:0xf bank_mask:0xf
	ds_read_b128 v[84:87], v27 offset:21248
	ds_read_b128 v[88:91], v27 offset:8448
	ds_read_b32 v92, v49 offset:8448
	v_pk_fma_f32 v[4:5], v[38:39], v[112:113], v[120:121] op_sel_hi:[1,0,1]
	v_pk_fma_f32 v[2:3], v[36:37], v[112:113], v[118:119] op_sel_hi:[1,0,1]
	s_waitcnt lgkmcnt(6)
	v_pk_mul_f32 v[114:115], v[4:5], v[52:53]
	v_pk_mul_f32 v[116:117], v[4:5], v[46:47]
	v_pk_fma_f32 v[114:115], v[2:3], v[50:51], v[114:115]
	v_pk_fma_f32 v[116:117], v[2:3], v[44:45], v[116:117]
	v_add_f32_e32 v112, v114, v115
	v_add_f32_e32 v103, v116, v117
	v_pk_mul_f32 v[118:119], v[62:63], v[70:71] op_sel_hi:[1,0]
	v_add_f32_dpp v112, v112, v112 row_ror:8 row_mask:0xf bank_mask:0xf
	v_pk_mul_f32 v[120:121], v[64:65], v[70:71] op_sel_hi:[1,0]
	v_pk_fma_f32 v[118:119], v[2:3], v[54:55], v[118:119]
	v_add_f32_dpp v112, v112, v112 row_ror:4 row_mask:0xf bank_mask:0xf
	v_pk_fma_f32 v[120:121], v[4:5], v[56:57], v[120:121]
	ds_read_b128 v[6:9], v27 offset:9472
	v_add_f32_dpp v112, v112, v112 row_ror:2 row_mask:0xf bank_mask:0xf
	ds_read_b128 v[10:13], v27 offset:21504
	ds_read_b128 v[14:17], v27 offset:21760
	v_add_f32_dpp v112, v112, v112 row_ror:1 row_mask:0xf bank_mask:0xf
	ds_read_b128 v[18:21], v27 offset:22016
	ds_read_b128 v[22:25], v27 offset:9216
	ds_read_b32 v26, v49 offset:9216
	v_pk_fma_f32 v[4:5], v[60:61], v[112:113], v[120:121] op_sel_hi:[1,0,1]
	v_pk_fma_f32 v[2:3], v[58:59], v[112:113], v[118:119] op_sel_hi:[1,0,1]
	s_waitcnt lgkmcnt(6)
	v_pk_mul_f32 v[114:115], v[4:5], v[74:75]
	v_pk_mul_f32 v[116:117], v[4:5], v[68:69]
	v_pk_fma_f32 v[114:115], v[2:3], v[72:73], v[114:115]
	v_pk_fma_f32 v[116:117], v[2:3], v[66:67], v[116:117]
	v_add_f32_e32 v112, v114, v115
	v_add_f32_e32 v104, v116, v117
	v_pk_mul_f32 v[118:119], v[84:85], v[92:93] op_sel_hi:[1,0]
	v_add_f32_dpp v112, v112, v112 row_ror:8 row_mask:0xf bank_mask:0xf
	v_pk_mul_f32 v[120:121], v[86:87], v[92:93] op_sel_hi:[1,0]
	v_pk_fma_f32 v[118:119], v[2:3], v[76:77], v[118:119]
	v_add_f32_dpp v112, v112, v112 row_ror:4 row_mask:0xf bank_mask:0xf
	v_pk_fma_f32 v[120:121], v[4:5], v[78:79], v[120:121]
	ds_read_b128 v[28:31], v27 offset:10240
	v_add_f32_dpp v112, v112, v112 row_ror:2 row_mask:0xf bank_mask:0xf
	ds_read_b128 v[32:35], v27 offset:22272
	ds_read_b128 v[36:39], v27 offset:22528
	v_add_f32_dpp v112, v112, v112 row_ror:1 row_mask:0xf bank_mask:0xf
	ds_read_b128 v[40:43], v27 offset:22784
	ds_read_b128 v[44:47], v27 offset:9984
	ds_read_b32 v48, v49 offset:9984
	v_pk_fma_f32 v[4:5], v[82:83], v[112:113], v[120:121] op_sel_hi:[1,0,1]
	v_pk_fma_f32 v[2:3], v[80:81], v[112:113], v[118:119] op_sel_hi:[1,0,1]
	s_waitcnt lgkmcnt(6)
	v_pk_mul_f32 v[114:115], v[4:5], v[8:9]
	v_pk_mul_f32 v[116:117], v[4:5], v[90:91]
	v_pk_fma_f32 v[114:115], v[2:3], v[6:7], v[114:115]
	v_pk_fma_f32 v[116:117], v[2:3], v[88:89], v[116:117]
	v_add_f32_e32 v112, v114, v115
	v_add_f32_e32 v105, v116, v117
	v_pk_mul_f32 v[118:119], v[18:19], v[26:27] op_sel_hi:[1,0]
	v_add_f32_dpp v112, v112, v112 row_ror:8 row_mask:0xf bank_mask:0xf
	v_pk_mul_f32 v[120:121], v[20:21], v[26:27] op_sel_hi:[1,0]
	v_pk_fma_f32 v[118:119], v[2:3], v[10:11], v[118:119]
	v_add_f32_dpp v112, v112, v112 row_ror:4 row_mask:0xf bank_mask:0xf
	v_pk_fma_f32 v[120:121], v[4:5], v[12:13], v[120:121]
	ds_read_b128 v[50:53], v27 offset:11008
	v_add_f32_dpp v112, v112, v112 row_ror:2 row_mask:0xf bank_mask:0xf
	ds_read_b128 v[54:57], v27 offset:23040
	ds_read_b128 v[58:61], v27 offset:23296
	v_add_f32_dpp v112, v112, v112 row_ror:1 row_mask:0xf bank_mask:0xf
	ds_read_b128 v[62:65], v27 offset:23552
	ds_read_b128 v[66:69], v27 offset:10752
	ds_read_b32 v70, v49 offset:10752
	v_pk_fma_f32 v[4:5], v[16:17], v[112:113], v[120:121] op_sel_hi:[1,0,1]
	v_pk_fma_f32 v[2:3], v[14:15], v[112:113], v[118:119] op_sel_hi:[1,0,1]
	s_waitcnt lgkmcnt(6)
	v_pk_mul_f32 v[114:115], v[4:5], v[30:31]
	v_pk_mul_f32 v[116:117], v[4:5], v[24:25]
	v_pk_fma_f32 v[114:115], v[2:3], v[28:29], v[114:115]
	v_pk_fma_f32 v[116:117], v[2:3], v[22:23], v[116:117]
	v_add_f32_e32 v112, v114, v115
	v_add_f32_e32 v106, v116, v117
	v_pk_mul_f32 v[118:119], v[40:41], v[48:49] op_sel_hi:[1,0]
	v_add_f32_dpp v112, v112, v112 row_ror:8 row_mask:0xf bank_mask:0xf
	v_pk_mul_f32 v[120:121], v[42:43], v[48:49] op_sel_hi:[1,0]
	v_pk_fma_f32 v[118:119], v[2:3], v[32:33], v[118:119]
	v_add_f32_dpp v112, v112, v112 row_ror:4 row_mask:0xf bank_mask:0xf
	v_pk_fma_f32 v[120:121], v[4:5], v[34:35], v[120:121]
	ds_read_b128 v[72:75], v27 offset:11776
	v_add_f32_dpp v112, v112, v112 row_ror:2 row_mask:0xf bank_mask:0xf
	ds_read_b128 v[76:79], v27 offset:23808
	ds_read_b128 v[80:83], v27 offset:24064
	v_add_f32_dpp v112, v112, v112 row_ror:1 row_mask:0xf bank_mask:0xf
	ds_read_b128 v[84:87], v27 offset:24320
	ds_read_b128 v[88:91], v27 offset:11520
	ds_read_b32 v92, v49 offset:11520
	v_pk_fma_f32 v[4:5], v[38:39], v[112:113], v[120:121] op_sel_hi:[1,0,1]
	v_pk_fma_f32 v[2:3], v[36:37], v[112:113], v[118:119] op_sel_hi:[1,0,1]
	s_waitcnt lgkmcnt(6)
	v_pk_mul_f32 v[114:115], v[4:5], v[52:53]
	v_pk_mul_f32 v[116:117], v[4:5], v[46:47]
	v_pk_fma_f32 v[114:115], v[2:3], v[50:51], v[114:115]
	v_pk_fma_f32 v[116:117], v[2:3], v[44:45], v[116:117]
	v_add_f32_e32 v112, v114, v115
	v_add_f32_e32 v107, v116, v117
	v_pk_mul_f32 v[118:119], v[62:63], v[70:71] op_sel_hi:[1,0]
	v_add_f32_dpp v112, v112, v112 row_ror:8 row_mask:0xf bank_mask:0xf
	v_pk_mul_f32 v[120:121], v[64:65], v[70:71] op_sel_hi:[1,0]
	v_pk_fma_f32 v[118:119], v[2:3], v[54:55], v[118:119]
	v_add_f32_dpp v112, v112, v112 row_ror:4 row_mask:0xf bank_mask:0xf
	v_pk_fma_f32 v[120:121], v[4:5], v[56:57], v[120:121]
	ds_read_b128 v[6:9], v71 offset:256
	v_add_f32_dpp v112, v112, v112 row_ror:2 row_mask:0xf bank_mask:0xf
	ds_read_b128 v[10:13], v71 offset:12288
	ds_read_b128 v[14:17], v71 offset:12544
	v_add_f32_dpp v112, v112, v112 row_ror:1 row_mask:0xf bank_mask:0xf
	ds_read_b128 v[18:21], v71 offset:12800
	ds_read_b128 v[22:25], v71 offset:0
	ds_read_b32 v26, v93 offset:0
	v_pk_fma_f32 v[4:5], v[60:61], v[112:113], v[120:121] op_sel_hi:[1,0,1]
	v_pk_fma_f32 v[2:3], v[58:59], v[112:113], v[118:119] op_sel_hi:[1,0,1]
	s_waitcnt lgkmcnt(6)
	v_pk_mul_f32 v[114:115], v[4:5], v[74:75]
	v_pk_mul_f32 v[116:117], v[4:5], v[68:69]
	v_pk_fma_f32 v[114:115], v[2:3], v[72:73], v[114:115]
	v_pk_fma_f32 v[116:117], v[2:3], v[66:67], v[116:117]
	v_add_f32_e32 v112, v114, v115
	v_add_f32_e32 v108, v116, v117
	v_pk_mul_f32 v[118:119], v[84:85], v[92:93] op_sel_hi:[1,0]
	v_add_f32_dpp v112, v112, v112 row_ror:8 row_mask:0xf bank_mask:0xf
	v_pk_mul_f32 v[120:121], v[86:87], v[92:93] op_sel_hi:[1,0]
	v_pk_fma_f32 v[118:119], v[2:3], v[76:77], v[118:119]
	v_add_f32_dpp v112, v112, v112 row_ror:4 row_mask:0xf bank_mask:0xf
	v_pk_fma_f32 v[120:121], v[4:5], v[78:79], v[120:121]
	ds_read_b128 v[28:31], v71 offset:1024
	v_add_f32_dpp v112, v112, v112 row_ror:2 row_mask:0xf bank_mask:0xf
	ds_read_b128 v[32:35], v71 offset:13056
	ds_read_b128 v[36:39], v71 offset:13312
	v_add_f32_dpp v112, v112, v112 row_ror:1 row_mask:0xf bank_mask:0xf
	ds_read_b128 v[40:43], v71 offset:13568
	ds_read_b128 v[44:47], v71 offset:768
	ds_read_b32 v48, v93 offset:768
	v_pk_fma_f32 v[4:5], v[82:83], v[112:113], v[120:121] op_sel_hi:[1,0,1]
	v_pk_fma_f32 v[2:3], v[80:81], v[112:113], v[118:119] op_sel_hi:[1,0,1]
	v_pk_mul_f32 v[116:117], v[4:5], v[90:91]
	s_mov_b32 s8, s9
	v_pk_fma_f32 v[116:117], v[2:3], v[88:89], v[116:117]
	v_mov_b32_e32 v27, v71
	v_add_f32_e32 v109, v116, v117
	v_mov_b32_e32 v49, v93
	v_add_f32_dpp v94, v94, v94 row_mirror row_mask:0xf bank_mask:0x3
	v_add_f32_dpp v94, v102, v102 row_mirror row_mask:0xf bank_mask:0xc
	v_add_f32_dpp v95, v95, v95 row_mirror row_mask:0xf bank_mask:0x3
	v_add_f32_dpp v95, v103, v103 row_mirror row_mask:0xf bank_mask:0xc
	v_add_f32_dpp v96, v96, v96 row_mirror row_mask:0xf bank_mask:0x3
	v_add_f32_dpp v96, v104, v104 row_mirror row_mask:0xf bank_mask:0xc
	v_add_f32_dpp v97, v97, v97 row_mirror row_mask:0xf bank_mask:0x3
	v_add_f32_dpp v97, v105, v105 row_mirror row_mask:0xf bank_mask:0xc
	v_add_f32_dpp v98, v98, v98 row_mirror row_mask:0xf bank_mask:0x3
	v_add_f32_dpp v98, v106, v106 row_mirror row_mask:0xf bank_mask:0xc
	v_add_f32_dpp v99, v99, v99 row_mirror row_mask:0xf bank_mask:0x3
	v_add_f32_dpp v99, v107, v107 row_mirror row_mask:0xf bank_mask:0xc
	v_add_f32_dpp v100, v100, v100 row_mirror row_mask:0xf bank_mask:0x3
	v_add_f32_dpp v100, v108, v108 row_mirror row_mask:0xf bank_mask:0xc
	v_add_f32_dpp v101, v101, v101 row_mirror row_mask:0xf bank_mask:0x3
	v_add_f32_dpp v101, v109, v109 row_mirror row_mask:0xf bank_mask:0xc
	v_add_f32_dpp v94, v94, v94 row_half_mirror row_mask:0xf bank_mask:0x5
	v_add_f32_dpp v94, v98, v98 row_half_mirror row_mask:0xf bank_mask:0xa
	v_add_f32_dpp v95, v95, v95 row_half_mirror row_mask:0xf bank_mask:0x5
	v_add_f32_dpp v95, v99, v99 row_half_mirror row_mask:0xf bank_mask:0xa
	v_add_f32_dpp v96, v96, v96 row_half_mirror row_mask:0xf bank_mask:0x5
	v_add_f32_dpp v96, v100, v100 row_half_mirror row_mask:0xf bank_mask:0xa
	v_add_f32_dpp v97, v97, v97 row_half_mirror row_mask:0xf bank_mask:0x5
	v_add_f32_dpp v97, v101, v101 row_half_mirror row_mask:0xf bank_mask:0xa
	v_cndmask_b32_e64 v122, v94, v96, s[10:11]
	v_cndmask_b32_e64 v123, v96, v94, s[10:11]
	v_cndmask_b32_e64 v98, v97, v95, s[10:11]
	v_cndmask_b32_e64 v99, v95, v97, s[10:11]
	v_add_f32_dpp v122, v123, v122 quad_perm:[2,3,0,1] row_mask:0xf bank_mask:0xf
	v_add_f32_dpp v99, v98, v99 quad_perm:[2,3,0,1] row_mask:0xf bank_mask:0xf
	s_nop 0
	v_cndmask_b32_e64 v100, v99, v122, s[14:15]
	v_cndmask_b32_e64 v101, v122, v99, s[14:15]
	s_sub_u32 s1, s1, 1
	s_nop 0
	v_add_f32_dpp v101, v100, v101 quad_perm:[1,0,3,2] row_mask:0xf bank_mask:0xf
	s_nop 0
	global_store_dword v111, v101, s[4:5]
	s_add_u32 s4, s4, s6
	s_addc_u32 s5, s5, s7
	s_cmp_lg_u32 s1, 0
	s_cbranch_scc1 .Lss_c_loop
	s_waitcnt lgkmcnt(0)
	s_barrier
	s_branch .Lss_next
.Lss_loader:
	s_sub_u32 s11, s0, 4
	s_add_u32 s22, s20, 16
	s_mul_i32 s22, s22, 0xc0000
	s_cmp_lt_u32 s11, 2
	s_cbranch_scc1 .Lss_ld_recs
	v_readlane_b32 s4, v253, 30
	v_readlane_b32 s5, v253, 31
	s_mul_i32 s23, s21, 0x1800000
	s_add_u32 s22, s22, s23
	s_branch .Lss_ld_base
.Lss_ld_recs:
	v_readlane_b32 s4, v253, 28
	v_readlane_b32 s5, v253, 29
.Lss_ld_base:
	s_nop 0
	s_add_u32 s4, s4, s22
	s_addc_u32 s5, s5, 0
	s_cmp_eq_u32 s21, 0
	s_cbranch_scc1 .Lss_ld_fwd
	s_add_u32 s4, s4, 0xbd000
	s_addc_u32 s5, s5, 0
	s_mov_b32 s6, 0xffffd000
	s_mov_b32 s7, -1
	s_branch .Lss_ld_dirdone
.Lss_ld_fwd:
	s_mov_b32 s6, 0x3000
	s_mov_b32 s7, 0
.Lss_ld_dirdone:
	v_and_b32_e32 v8, 63, v0
	s_and_b32 s23, s11, 1
	v_lshlrev_b32_e32 v8, 4, v8
	s_mul_i32 s23, s23, 0x1800
	s_nop 0
	v_add_u32_e32 v8, s23, v8
	v_mov_b32_e32 v9, v8
	v_lshrrev_b32_e32 v10, 8, v9
	v_mul_u32_u24_e32 v10, 0xaaab, v10
	v_lshrrev_b32_e32 v10, 17, v10
	v_mul_u32_u24_e32 v11, 0x600, v10
	v_sub_u32_e32 v11, 0x2d00, v11
	v_mul_lo_u32 v11, v11, s21
	v_add_u32_e32 v2, v9, v11
	v_add_u32_e32 v9, 0x400, v8
	v_lshrrev_b32_e32 v10, 8, v9
	v_mul_u32_u24_e32 v10, 0xaaab, v10
	v_lshrrev_b32_e32 v10, 17, v10
	v_mul_u32_u24_e32 v11, 0x600, v10
	v_sub_u32_e32 v11, 0x2d00, v11
	v_mul_lo_u32 v11, v11, s21
	v_add_u32_e32 v3, v9, v11
	v_add_u32_e32 v9, 0x800, v8
	v_lshrrev_b32_e32 v10, 8, v9
	v_mul_u32_u24_e32 v10, 0xaaab, v10
	v_lshrrev_b32_e32 v10, 17, v10
	v_mul_u32_u24_e32 v11, 0x600, v10
	v_sub_u32_e32 v11, 0x2d00, v11
	v_mul_lo_u32 v11, v11, s21
	v_add_u32_e32 v4, v9, v11
	v_add_u32_e32 v9, 0xc00, v8
	v_lshrrev_b32_e32 v10, 8, v9
	v_mul_u32_u24_e32 v10, 0xaaab, v10
	v_lshrrev_b32_e32 v10, 17, v10
	v_mul_u32_u24_e32 v11, 0x600, v10
	v_sub_u32_e32 v11, 0x2d00, v11
	v_mul_lo_u32 v11, v11, s21
	v_add_u32_e32 v5, v9, v11
	v_add_u32_e32 v9, 0x1000, v8
	v_lshrrev_b32_e32 v10, 8, v9
	v_mul_u32_u24_e32 v10, 0xaaab, v10
	v_lshrrev_b32_e32 v10, 17, v10
	v_mul_u32_u24_e32 v11, 0x600, v10
	v_sub_u32_e32 v11, 0x2d00, v11
	v_mul_lo_u32 v11, v11, s21
	v_add_u32_e32 v6, v9, v11
	v_add_u32_e32 v9, 0x1400, v8
	v_lshrrev_b32_e32 v10, 8, v9
	v_mul_u32_u24_e32 v10, 0xaaab, v10
	v_lshrrev_b32_e32 v10, 17, v10
	v_mul_u32_u24_e32 v11, 0x600, v10
	v_sub_u32_e32 v11, 0x2d00, v11
	v_mul_lo_u32 v11, v11, s21
	v_add_u32_e32 v7, v9, v11
	s_mul_i32 s8, s11, 0x1800
	s_add_u32 s8, s8, 0xf0
	s_mov_b32 s9, 0
	s_mov_b32 s10, 0
	s_mov_b32 m0, s8
	s_nop 0
	global_load_lds_dwordx4 v2, s[4:5]
	s_add_u32 m0, s8, 0x400
	s_nop 0
	global_load_lds_dwordx4 v3, s[4:5]
	s_add_u32 m0, s8, 0x800
	s_nop 0
	global_load_lds_dwordx4 v4, s[4:5]
	s_add_u32 m0, s8, 0xc00
	s_nop 0
	global_load_lds_dwordx4 v5, s[4:5]
	s_add_u32 m0, s8, 0x1000
	s_nop 0
	global_load_lds_dwordx4 v6, s[4:5]
	s_add_u32 m0, s8, 0x1400
	s_nop 0
	global_load_lds_dwordx4 v7, s[4:5]
	s_cmp_lt_u32 s10, 63
	s_cselect_b32 s22, s6, 0
	s_cselect_b32 s23, s7, 0
	s_cselect_b32 s24, 1, 0
	s_add_u32 s4, s4, s22
	s_addc_u32 s5, s5, s23
	s_add_u32 s10, s10, s24
	s_add_u32 s9, s9, 1
	s_add_u32 s8, s8, 0x6000
	s_cmp_eq_u32 s9, 5
	s_cselect_b32 s22, 0x1e000, 0
	s_cselect_b32 s9, 0, s9
	s_sub_u32 s8, s8, s22
	s_mov_b32 m0, s8
	s_nop 0
	global_load_lds_dwordx4 v2, s[4:5]
	s_add_u32 m0, s8, 0x400
	s_nop 0
	global_load_lds_dwordx4 v3, s[4:5]
	s_add_u32 m0, s8, 0x800
	s_nop 0
	global_load_lds_dwordx4 v4, s[4:5]
	s_add_u32 m0, s8, 0xc00
	s_nop 0
	global_load_lds_dwordx4 v5, s[4:5]
	s_add_u32 m0, s8, 0x1000
	s_nop 0
	global_load_lds_dwordx4 v6, s[4:5]
	s_add_u32 m0, s8, 0x1400
	s_nop 0
	global_load_lds_dwordx4 v7, s[4:5]
	s_cmp_lt_u32 s10, 63
	s_cselect_b32 s22, s6, 0
	s_cselect_b32 s23, s7, 0
	s_cselect_b32 s24, 1, 0
	s_add_u32 s4, s4, s22
	s_addc_u32 s5, s5, s23
	s_add_u32 s10, s10, s24
	s_add_u32 s9, s9, 1
	s_add_u32 s8, s8, 0x6000
	s_cmp_eq_u32 s9, 5
	s_cselect_b32 s22, 0x1e000, 0
	s_cselect_b32 s9, 0, s9
	s_sub_u32 s8, s8, s22
	s_mov_b32 m0, s8
	s_nop 0
	global_load_lds_dwordx4 v2, s[4:5]
	s_add_u32 m0, s8, 0x400
	s_nop 0
	global_load_lds_dwordx4 v3, s[4:5]
	s_add_u32 m0, s8, 0x800
	s_nop 0
	global_load_lds_dwordx4 v4, s[4:5]
	s_add_u32 m0, s8, 0xc00
	s_nop 0
	global_load_lds_dwordx4 v5, s[4:5]
	s_add_u32 m0, s8, 0x1000
	s_nop 0
	global_load_lds_dwordx4 v6, s[4:5]
	s_add_u32 m0, s8, 0x1400
	s_nop 0
	global_load_lds_dwordx4 v7, s[4:5]
	s_cmp_lt_u32 s10, 63
	s_cselect_b32 s22, s6, 0
	s_cselect_b32 s23, s7, 0
	s_cselect_b32 s24, 1, 0
	s_add_u32 s4, s4, s22
	s_addc_u32 s5, s5, s23
	s_add_u32 s10, s10, s24
	s_add_u32 s9, s9, 1
	s_add_u32 s8, s8, 0x6000
	s_cmp_eq_u32 s9, 5
	s_cselect_b32 s22, 0x1e000, 0
	s_cselect_b32 s9, 0, s9
	s_sub_u32 s8, s8, s22
	s_mov_b32 m0, s8
	s_nop 0
	global_load_lds_dwordx4 v2, s[4:5]
	s_add_u32 m0, s8, 0x400
	s_nop 0
	global_load_lds_dwordx4 v3, s[4:5]
	s_add_u32 m0, s8, 0x800
	s_nop 0
	global_load_lds_dwordx4 v4, s[4:5]
	s_add_u32 m0, s8, 0xc00
	s_nop 0
	global_load_lds_dwordx4 v5, s[4:5]
	s_add_u32 m0, s8, 0x1000
	s_nop 0
	global_load_lds_dwordx4 v6, s[4:5]
	s_add_u32 m0, s8, 0x1400
	s_nop 0
	global_load_lds_dwordx4 v7, s[4:5]
	s_cmp_lt_u32 s10, 63
	s_cselect_b32 s22, s6, 0
	s_cselect_b32 s23, s7, 0
	s_cselect_b32 s24, 1, 0
	s_add_u32 s4, s4, s22
	s_addc_u32 s5, s5, s23
	s_add_u32 s10, s10, s24
	s_add_u32 s9, s9, 1
	s_add_u32 s8, s8, 0x6000
	s_cmp_eq_u32 s9, 5
	s_cselect_b32 s22, 0x1e000, 0
	s_cselect_b32 s9, 0, s9
	s_sub_u32 s8, s8, s22
	s_waitcnt vmcnt(12)
	s_barrier
	s_mov_b32 s1, 64
.Lss_ld_loop:
	s_waitcnt vmcnt(12)
	s_barrier
	s_mov_b32 m0, s8
	s_nop 0
	global_load_lds_dwordx4 v2, s[4:5]
	s_add_u32 m0, s8, 0x400
	s_nop 0
	global_load_lds_dwordx4 v3, s[4:5]
	s_add_u32 m0, s8, 0x800
	s_nop 0
	global_load_lds_dwordx4 v4, s[4:5]
	s_add_u32 m0, s8, 0xc00
	s_nop 0
	global_load_lds_dwordx4 v5, s[4:5]
	s_add_u32 m0, s8, 0x1000
	s_nop 0
	global_load_lds_dwordx4 v6, s[4:5]
	s_add_u32 m0, s8, 0x1400
	s_nop 0
	global_load_lds_dwordx4 v7, s[4:5]
	s_cmp_lt_u32 s10, 63
	s_cselect_b32 s22, s6, 0
	s_cselect_b32 s23, s7, 0
	s_cselect_b32 s24, 1, 0
	s_add_u32 s4, s4, s22
	s_addc_u32 s5, s5, s23
	s_add_u32 s10, s10, s24
	s_add_u32 s9, s9, 1
	s_add_u32 s8, s8, 0x6000
	s_cmp_eq_u32 s9, 5
	s_cselect_b32 s22, 0x1e000, 0
	s_cselect_b32 s9, 0, s9
	s_sub_u32 s8, s8, s22
	s_sub_u32 s1, s1, 1
	s_cmp_lg_u32 s1, 0
	s_cbranch_scc1 .Lss_ld_loop
	s_waitcnt vmcnt(0)
	s_barrier
.Lss_next:
	s_add_u32 s71, s71, s70
	s_branch .Lss_task_loop
.Lss_done:
.LBB0_597:
	v_readlane_b32 s0, v253, 53
	s_add_u32 s4, s0, s12
	v_readlane_b32 s0, v253, 54
	s_addc_u32 s5, s0, s13
	v_writelane_b32 v254, s4, 61
	s_lshl_b32 s0, s80, 2
	s_lshl_b32 s96, s80, 14
	v_writelane_b32 v254, s5, 62
	v_writelane_b32 v254, s0, 63
	s_lshl_b64 s[0:1], s[96:97], 2
	v_cmp_eq_u32_e64 s[8:9], 0, v1
	v_writelane_b32 v255, s0, 0
	v_readlane_b32 s79, v254, 50
	v_mov_b64_e32 v[132:133], 0x1ff
	v_writelane_b32 v255, s1, 1
	v_mov_b64_e32 v[134:135], 0x200
	s_waitcnt lgkmcnt(0)
	s_barrier
	s_branch .LBB0_601
